# non-temporal hint on the read-once f32 weight loads of the conversion loops
# baseline (speedup 1.0000x reference)
; #define LAS __attribute__((address_space(3)))
; DI float h2f(bf16_t v) { return (float)__builtin_bit_cast(_Float16, v); }
; DI float bf2f(bf16_t v) { return __uint_as_float(((unsigned)v) << 16); }
; DI int lane_id_() { int l; asm volatile("v_mbcnt_lo_u32_b32 %0, -1, 0\n\tv_mbcnt_hi_u32_b32 %0, -1, %0" : "=v"(l)); return l; }
;     ...
;   int tid_ = wv * 64 + lane_id_(); asm volatile("" : "+v"(tid_)); const int tid = tid_, kr = tid >> 4, nc = (tid & 15) * 4;
;   const bool colok = (n0 + nc) < nvalid;
;   float s1[4] = {0.f, 0.f, 0.f, 0.f}, s2[4] = {0.f, 0.f, 0.f, 0.f};
;   f32x4 w[2];
; #pragma unroll
;   for (int rr = 0; rr < 2; ++rr) w[rr] = colok ? *(const f32x4*)(src + (size_t)(kbeg + kr + rr * 32) * ldn + n0 + nc) : (f32x4){0.f, 0.f, 0.f, 0.f};
;   for (int k0 = kbeg; k0 < kend; k0 += 64) {
;     lds_barrier();
; #pragma unroll
;     for (int rr = 0; rr < 2; ++rr) { const int k = k0 + kr + rr * 32; const float gk = g ? g[k] : 1.0f, bk = b ? b[k] : 0.0f;
; #pragma unroll
;       for (int j = 0; j < 4; ++j) { const bf16_t v = perm ? f2h(w[rr][j] * gk) : f2bf(w[rr][j] * gk); tile[(nc + j) * 72 + kr + rr * 32] = v; s1[j] += perm ? h2f(v) : bf2f(v); s2[j] += bk * w[rr][j]; } }
;     if (k0 + 64 < kend) {
; #pragma unroll
;       for (int rr = 0; rr < 2; ++rr) w[rr] = colok ? *(const f32x4*)(src + (size_t)(k0 + 64 + kr + rr * 32) * ldn + n0 + nc) : (f32x4){0.f, 0.f, 0.f, 0.f};
;     }
;     lds_barrier();
;     { const int n = tid >> 3, kc = (tid & 7) * 8; const int cc = n & 31, slot = (n & 32) + (perm ? 16 * ((cc >> 2) & 1) + 4 * (cc >> 3) + (cc & 3) : cc);
;       *(u32x4*)(dst + (size_t)(dstrow0 + slot) * K + k0 + kc) = *(const LAS u32x4*)(tile + n * 72 + kc); }
; DI void convert_phase(int wv, const P& p_, int L, LAS unsigned char* lds) {
;     ...
;       const int s = j - 272 - nin - 16;
;       if (s < 4) { const int kv = s >> 1, st = s & 1; float* pb = (float*)(ws + C_POSB) + kv * 256;
;         conv_strip(wv, lds, p.nsa_w1 + ((size_t)slot * 2 + kv) * 2048 * 128, 128, 2048, st * 64, 128, (bf16_t*)(ws + W_W1T) + (size_t)kv * 128 * 2048, st * 64, nullptr, p.nsa_pos + ((size_t)slot * 2 + kv) * 2048, pb + 128, pb, false); }
;       else { const int kv = s - 4; conv_strip(wv, lds, p.nsa_w2 + ((size_t)slot * 2 + kv) * 128 * 64, 64, 128, 0, 64, (bf16_t*)(ws + W_W2T) + (size_t)kv * 64 * 128, 0, nullptr, nullptr, nullptr, nullptr, false); }
.Lconv_noremap:
	s_cmpk_gt_i32 s87, 0x10f
	s_mov_b64 s[0:1], -1
	s_cbranch_scc0 .LBB0_103
	s_cmp_ge_i32 s87, s50
	s_mov_b64 s[8:9], 0x100
	s_cbranch_scc0 .LBB0_77
	s_sub_i32 s27, s87, s41
	s_cmp_ge_i32 s87, s51
	s_cbranch_scc0 .LBB0_58
	s_cmpk_gt_u32 s27, 0x123
	s_cbranch_scc0 .LBB0_44
	s_add_i32 s84, s27, 0xfffffedc
	s_waitcnt vmcnt(1)
	v_mbcnt_lo_u32_b32 v0, -1, 0
	v_mbcnt_hi_u32_b32 v0, -1, v0
	s_lshl_b64 s[0:1], s[84:85], 15
	v_add_u32_e32 v18, s69, v0
	v_readlane_b32 s6, v255, 41
	s_add_u32 s0, s6, s0
	v_lshlrev_b32_e32 v0, 2, v18
	v_readlane_b32 s6, v255, 43
	v_ashrrev_i32_e32 v16, 4, v18
	v_and_b32_e32 v20, 60, v0
	s_addc_u32 s1, s6, s1
	v_lshlrev_b32_e32 v0, 2, v20
	v_mov_b32_e32 v1, v32
	v_ashrrev_i32_e32 v17, 31, v16
	v_lshl_add_u64 v[0:1], s[0:1], 0, v[0:1]
	v_lshlrev_b64 v[2:3], 8, v[16:17]
	v_lshl_add_u64 v[12:13], v[0:1], 0, v[2:3]
	s_movk_i32 s0, 0x2000
	v_add_co_u32_e32 v4, vcc, s0, v12
	global_load_dwordx4 v[0:3], v[12:13], off nt
	s_nop 0
	v_addc_co_u32_e32 v5, vcc, 0, v13, vcc
	global_load_dwordx4 v[4:7], v[4:5], off nt
	s_movk_i32 s0, 0x4000
	v_add_co_u32_e32 v8, vcc, s0, v12
	s_movk_i32 s0, 0x6000
	s_nop 0
	v_addc_co_u32_e32 v9, vcc, 0, v13, vcc
	s_waitcnt lgkmcnt(0)
	s_barrier
	v_add_co_u32_e32 v12, vcc, s0, v12
	global_load_dwordx4 v[8:11], v[8:9], off nt
	s_nop 0
	v_addc_co_u32_e32 v13, vcc, 0, v13, vcc
	global_load_dwordx4 v[12:15], v[12:13], off nt
	s_lshl_b64 s[0:1], s[84:85], 14
	v_readlane_b32 s6, v255, 48
	s_add_u32 s0, s6, s0
	v_lshlrev_b32_e32 v22, 1, v16
	v_mul_u32_u24_e32 v20, 0x90, v20
	v_add3_u32 v20, 0, v22, v20
	v_ashrrev_i32_e32 v21, 3, v18
	v_lshlrev_b32_e32 v18, 4, v18
	v_mul_lo_u32 v16, v21, s90
	v_and_b32_e32 v18, 0x70, v18
	v_add3_u32 v23, 0, v16, v18
	v_lshlrev_b32_e32 v21, 8, v21
	v_readlane_b32 s6, v255, 50
	v_mov_b32_e32 v17, v32
	s_addc_u32 s1, s6, s1
	v_and_b32_e32 v16, 0x3f00, v21
	v_mov_b32_e32 v19, v32
	v_lshl_add_u64 v[16:17], s[0:1], 0, v[16:17]
	v_lshl_add_u64 v[16:17], v[16:17], 0, v[18:19]
	s_waitcnt vmcnt(3)
	v_cvt_pk_bf16_f32 v0, v0, s0
	v_cvt_pk_bf16_f32 v1, v1, s0
	v_cvt_pk_bf16_f32 v2, v2, s0
	v_cvt_pk_bf16_f32 v3, v3, s0
	ds_write_b16 v20, v0
	ds_write_b16 v20, v1 offset:144
	ds_write_b16 v20, v2 offset:288
	ds_write_b16 v20, v3 offset:432
	s_waitcnt vmcnt(2)
	v_cvt_pk_bf16_f32 v0, v4, s0
	v_cvt_pk_bf16_f32 v1, v5, s0
	v_cvt_pk_bf16_f32 v2, v6, s0
	v_cvt_pk_bf16_f32 v3, v7, s0
	ds_write_b16 v20, v0 offset:64
	ds_write_b16 v20, v1 offset:208
	ds_write_b16 v20, v2 offset:352
	ds_write_b16 v20, v3 offset:496
	s_waitcnt lgkmcnt(0)
	s_barrier
	ds_read_b128 v[0:3], v23
	s_waitcnt vmcnt(1)
	v_cvt_pk_bf16_f32 v4, v8, s0
	v_cvt_pk_bf16_f32 v5, v9, s0
	v_cvt_pk_bf16_f32 v6, v10, s0
	s_waitcnt lgkmcnt(0)
	global_store_dwordx4 v[16:17], v[0:3], off
	v_cvt_pk_bf16_f32 v7, v11, s0
	s_waitcnt vmcnt(1)
	v_cvt_pk_bf16_f32 v8, v12, s0
	v_cvt_pk_bf16_f32 v9, v13, s0
	v_cvt_pk_bf16_f32 v10, v14, s0
	v_cvt_pk_bf16_f32 v11, v15, s0
	s_waitcnt lgkmcnt(0)
	s_barrier
	ds_write_b16 v20, v4
	ds_write_b16 v20, v5 offset:144
	ds_write_b16 v20, v6 offset:288
	ds_write_b16 v20, v7 offset:432
	ds_write_b16 v20, v8 offset:64
	ds_write_b16 v20, v9 offset:208
	ds_write_b16 v20, v10 offset:352
	ds_write_b16 v20, v11 offset:496
	s_waitcnt lgkmcnt(0)
	s_barrier
	ds_read_b128 v[0:3], v23
	s_mov_b64 s[0:1], 0
	s_waitcnt lgkmcnt(0)
	global_store_dwordx4 v[16:17], v[0:3], off offset:128
	s_barrier
.LBB0_44:
	s_andn2_b64 vcc, exec, s[0:1]
	s_cbranch_vccnz .LBB0_57
	s_add_i32 s0, s27, 0xfffffee0
	s_ashr_i32 s0, s0, 1
	s_bfe_u32 s34, s86, 0x10006
	s_ashr_i32 s1, s0, 31
	s_lshl_b32 s35, s34, 8
	s_lshl_b64 s[6:7], s[0:1], 11
	v_readlane_b32 s4, v255, 32
	v_readlane_b32 s5, v255, 33
	s_add_u32 s6, s6, s4
	s_addc_u32 s7, s7, s5
	v_readlane_b32 s60, v252, 32
	s_lshl_b64 s[6:7], s[6:7], 9
	v_readlane_b32 s70, v252, 42
	v_readlane_b32 s69, v252, 41
	v_readlane_b32 s71, v252, 43
	s_add_u32 s30, s70, s6
	s_mov_b32 s69, s48
	s_addc_u32 s31, s71, s7
	s_lshl_b32 s6, s87, 6
	s_and_b32 s29, s6, 64
	s_waitcnt vmcnt(1)
	v_mbcnt_lo_u32_b32 v0, -1, 0
	v_mbcnt_hi_u32_b32 v0, -1, v0
	s_lshl_b64 s[6:7], s[0:1], 19
	v_add_u32_e32 v33, s69, v0
	s_lshl_b32 s36, s29, 2
	v_lshlrev_b32_e32 v0, 2, v33
	v_ashrrev_i32_e32 v24, 4, v33
	v_and_b32_e32 v10, 60, v0
	s_add_u32 s30, s30, s36
	s_addc_u32 s31, s31, 0
	v_lshlrev_b32_e32 v26, 2, v10
	v_mov_b32_e32 v27, v32
	v_ashrrev_i32_e32 v25, 31, v24
	v_lshl_add_u64 v[0:1], s[30:31], 0, v[26:27]
	v_lshlrev_b64 v[8:9], 9, v[24:25]
	v_lshl_add_u64 v[0:1], v[0:1], 0, v[8:9]
	s_movk_i32 s4, 0x4000
	v_add_co_u32_e32 v2, vcc, s4, v0
	v_ashrrev_i32_e32 v11, 3, v33
	s_nop 0
	v_addc_co_u32_e32 v3, vcc, 0, v1, vcc
	global_load_dwordx4 v[4:7], v[0:1], off nt
	s_nop 0
	global_load_dwordx4 v[0:3], v[2:3], off nt
	v_lshlrev_b32_e32 v14, 4, v33
	v_mul_lo_u32 v13, v11, s90
	v_and_b32_e32 v14, 0x70, v14
	v_lshlrev_b32_e32 v11, 12, v11
	v_add3_u32 v27, 0, v13, v14
	v_mul_u32_u24_e32 v13, 0x90, v10
	v_and_b32_e32 v10, 7, v33
	v_and_b32_e32 v11, 0x3f000, v11
	v_lshlrev_b32_e32 v10, 4, v10
	v_lshl_or_b32 v11, s34, 18, v11
	v_or3_b32 v10, s6, v10, v11
	v_mov_b32_e32 v11, s7
	v_lshl_add_u64 v[28:29], s[20:21], 0, v[10:11]
	s_lshl_b64 s[6:7], s[0:1], 20
	v_and_b32_e32 v10, 15, v33
	v_lshl_add_u64 v[8:9], s[6:7], 0, v[8:9]
	v_lshlrev_b32_e32 v10, 4, v10
	v_readlane_b32 s4, v255, 34
	s_lshl_b64 s[6:7], s[0:1], 13
	v_readlane_b32 s1, v255, 45
	v_or3_b32 v8, v8, s35, v10
	v_readlane_b32 s5, v255, 35
	s_add_u32 s6, s1, s6
	v_readlane_b32 s1, v255, 46
	v_lshl_add_u32 v12, v24, 1, 0
	v_lshl_add_u64 v[30:31], s[4:5], 0, v[8:9]
	s_addc_u32 s7, s1, s7
	v_mov_b32_e32 v8, 0
	v_readlane_b32 s4, v252, 52
	s_mov_b32 s30, 0
	v_lshl_add_u64 v[34:35], v[24:25], 2, s[6:7]
	v_add_u32_e32 v25, v12, v13
	v_mov_b32_e32 v9, v8
	v_mov_b32_e32 v10, v8
	v_mov_b32_e32 v11, v8
	v_mov_b32_e32 v12, v8
	v_mov_b32_e32 v13, v8
	v_mov_b32_e32 v14, v8
	v_mov_b32_e32 v15, v8
	v_readlane_b32 s5, v252, 53
	v_readlane_b32 s61, v252, 33
	v_readlane_b32 s62, v252, 34
	v_readlane_b32 s63, v252, 35
	v_readlane_b32 s64, v252, 36
	v_readlane_b32 s65, v252, 37
	v_readlane_b32 s66, v252, 38
	v_readlane_b32 s67, v252, 39
	v_readlane_b32 s68, v252, 40
	v_readlane_b32 s72, v252, 44
	v_readlane_b32 s73, v252, 45
	v_readlane_b32 s74, v252, 46
	v_readlane_b32 s75, v252, 47
	s_mov_b64 s[98:99], 0x8000
	s_mov_b64 s[100:101], 0x4000
	s_and_b64 vcc, exec, s[4:5]
	s_cbranch_vccz .Lc47_nb0
	global_load_dword v216, v[34:35], off offset:-128
	global_load_dword v217, v[34:35], off
.Lc47_nb0:
	v_add_co_u32_e32 v244, vcc, 0xffffc000, v30
	s_nop 1
	v_addc_co_u32_e32 v245, vcc, -1, v31, vcc
	global_load_dwordx4 v[244:247], v[244:245], off nt
	s_nop 0
	global_load_dwordx4 v[248:251], v[30:31], off nt
	s_waitcnt vmcnt(2)
	s_branch .LBB0_47

;     ...
;     if (k0 + 64 < kend) {
; #pragma unroll
;       for (int rr = 0; rr < 2; ++rr) w[rr] = colok ? *(const f32x4*)(src + (size_t)(k0 + 64 + kr + rr * 32) * ldn + n0 + nc) : (f32x4){0.f, 0.f, 0.f, 0.f};
;     }
.Lc47a_nbl:
	s_cmpk_lt_u32 s30, 0x780
	s_cbranch_scc0 .Lc47a_46
	v_lshl_add_u64 v[220:221], v[30:31], 0, s[100:101]
	v_lshl_add_u64 v[224:225], v[30:31], 0, s[98:99]
	global_load_dwordx4 v[220:223], v[220:221], off nt
	s_nop 0
	global_load_dwordx4 v[224:227], v[224:225], off nt

;     ...
;     if (k0 + 64 < kend) {
; #pragma unroll
;       for (int rr = 0; rr < 2; ++rr) w[rr] = colok ? *(const f32x4*)(src + (size_t)(k0 + 64 + kr + rr * 32) * ldn + n0 + nc) : (f32x4){0.f, 0.f, 0.f, 0.f};
;     }
.Lc47b_nbl:
	s_cmpk_lt_u32 s30, 0x780
	s_cbranch_scc0 .Lc47b_46
	v_lshl_add_u64 v[244:245], v[30:31], 0, s[100:101]
	v_lshl_add_u64 v[248:249], v[30:31], 0, s[98:99]
	global_load_dwordx4 v[244:247], v[244:245], off nt
	s_nop 0
	global_load_dwordx4 v[248:251], v[248:249], off nt

; #define LAS __attribute__((address_space(3)))
; DI float h2f(bf16_t v) { return (float)__builtin_bit_cast(_Float16, v); }
; DI float bf2f(bf16_t v) { return __uint_as_float(((unsigned)v) << 16); }
; DI int lane_id_() { int l; asm volatile("v_mbcnt_lo_u32_b32 %0, -1, 0\n\tv_mbcnt_hi_u32_b32 %0, -1, %0" : "=v"(l)); return l; }
; DI void lds_barrier() { asm volatile("s_waitcnt lgkmcnt(0)\n\ts_barrier" ::: "memory"); }
;     ...
;   int tid_ = wv * 64 + lane_id_(); asm volatile("" : "+v"(tid_)); const int tid = tid_, kr = tid >> 4, nc = (tid & 15) * 4;
;   const bool colok = (n0 + nc) < nvalid;
;   float s1[4] = {0.f, 0.f, 0.f, 0.f}, s2[4] = {0.f, 0.f, 0.f, 0.f};
;   f32x4 w[2];
; #pragma unroll
;   for (int rr = 0; rr < 2; ++rr) w[rr] = colok ? *(const f32x4*)(src + (size_t)(kbeg + kr + rr * 32) * ldn + n0 + nc) : (f32x4){0.f, 0.f, 0.f, 0.f};
;   for (int k0 = kbeg; k0 < kend; k0 += 64) {
;     lds_barrier();
; #pragma unroll
;     for (int rr = 0; rr < 2; ++rr) { const int k = k0 + kr + rr * 32; const float gk = g ? g[k] : 1.0f, bk = b ? b[k] : 0.0f;
; #pragma unroll
;       for (int j = 0; j < 4; ++j) { const bf16_t v = perm ? f2h(w[rr][j] * gk) : f2bf(w[rr][j] * gk); tile[(nc + j) * 72 + kr + rr * 32] = v; s1[j] += perm ? h2f(v) : bf2f(v); s2[j] += bk * w[rr][j]; } }
;     if (k0 + 64 < kend) {
; #pragma unroll
;       for (int rr = 0; rr < 2; ++rr) w[rr] = colok ? *(const f32x4*)(src + (size_t)(k0 + 64 + kr + rr * 32) * ldn + n0 + nc) : (f32x4){0.f, 0.f, 0.f, 0.f};
;     }
;     lds_barrier();
;     { const int n = tid >> 3, kc = (tid & 7) * 8; const int cc = n & 31, slot = (n & 32) + (perm ? 16 * ((cc >> 2) & 1) + 4 * (cc >> 3) + (cc & 3) : cc);
;       *(u32x4*)(dst + (size_t)(dstrow0 + slot) * K + k0 + kc) = *(const LAS u32x4*)(tile + n * 72 + kc); }
; DI void convert_phase(int wv, const P& p_, int L, LAS unsigned char* lds) {
;     ...
;       const int s = j - 272 - nin;
;       const float* src = kind == 0 ? p.nsa_wout + (size_t)slot * DM * DM : (kind == 1 ? p.hg_wout + (size_t)slot * DM * DM : p.swa_wout + (size_t)slot * DM * DM);
;       conv_strip(wv, lds, src, DM, DM, s * 64, DM, (bf16_t*)(ws + W_OUT), s * 64, nullptr, nullptr, nullptr, nullptr);
.LBB0_58:
	s_andn2_b64 vcc, exec, s[0:1]
	s_cbranch_vccnz .LBB0_76
	s_waitcnt vmcnt(1)
	v_mbcnt_lo_u32_b32 v0, -1, 0
	v_mbcnt_hi_u32_b32 v0, -1, v0
	s_lshl_b32 s0, s27, 6
	v_add_u32_e32 v13, s69, v0
	s_addk_i32 s0, 0xbc00
	v_lshlrev_b32_e32 v0, 2, v13
	v_and_b32_e32 v14, 60, v0
	v_or_b32_e32 v0, s0, v14
	s_movk_i32 s1, 0x400
	v_cmp_gt_i32_e64 s[6:7], s1, v0
	s_ashr_i32 s1, s0, 31
	s_lshl_b64 s[0:1], s[0:1], 2
	s_add_u32 s0, s33, s0
	v_ashrrev_i32_e32 v8, 4, v13
	s_addc_u32 s1, s76, s1
	v_lshlrev_b32_e32 v0, 2, v14
	v_mov_b32_e32 v1, v32
	v_lshl_add_u64 v[10:11], s[0:1], 0, v[0:1]
	v_mov_b32_e32 v0, 0
	v_ashrrev_i32_e32 v9, 31, v8
	v_mov_b32_e32 v4, 0
	v_mov_b32_e32 v5, 0
	v_mov_b32_e32 v6, 0
	v_mov_b32_e32 v7, 0
	s_and_saveexec_b64 s[0:1], s[6:7]
	s_cbranch_execz .LBB0_61
	v_lshlrev_b64 v[2:3], 12, v[8:9]
	v_lshl_add_u64 v[2:3], v[10:11], 0, v[2:3]
	global_load_dwordx4 v[4:7], v[2:3], off nt
.LBB0_61:
	s_or_b64 exec, exec, s[0:1]
	v_mov_b32_e32 v1, 0
	v_mov_b32_e32 v2, 0
	v_mov_b32_e32 v3, 0
	s_and_saveexec_b64 s[0:1], s[6:7]
	s_cbranch_execz .LBB0_63
	v_lshlrev_b64 v[0:1], 12, v[8:9]
	v_lshl_add_u64 v[0:1], v[10:11], 0, v[0:1]
	v_add_co_u32_e32 v0, vcc, 0x20000, v0
	s_nop 1
	v_addc_co_u32_e32 v1, vcc, 0, v1, vcc
	global_load_dwordx4 v[0:3], v[0:1], off nt
.LBB0_63:
	s_or_b64 exec, exec, s[0:1]
	v_ashrrev_i32_e32 v10, 3, v13
	v_lshrrev_b32_e32 v12, 1, v10
	v_lshlrev_b32_e32 v11, 2, v10
	v_and_b32_e32 v16, 12, v12
	v_mul_lo_u32 v12, v10, s90
	v_and_b32_e32 v10, 35, v10
	v_and_b32_e32 v11, 16, v11
	v_add_u32_e32 v10, s28, v10
	s_ashr_i32 s29, s28, 31
	v_lshlrev_b32_e32 v17, 4, v13
	v_add3_u32 v10, v10, v11, v16
	s_lshl_b64 s[0:1], s[28:29], 2
	v_and_b32_e32 v17, 0x70, v17
	v_ashrrev_i32_e32 v11, 31, v10
	v_lshl_add_u32 v15, v8, 1, 0
	v_add3_u32 v12, 0, v12, v17
	v_lshlrev_b64 v[8:9], 12, v[8:9]
	v_and_b32_e32 v17, 15, v13
	s_add_u32 s0, s45, s0
	v_lshlrev_b64 v[10:11], 11, v[10:11]
	v_and_b32_e32 v13, 7, v13
	v_mul_u32_u24_e32 v14, 0x90, v14
	v_lshl_or_b32 v8, v17, 4, v8
	s_addc_u32 s1, s57, s1
	v_lshl_or_b32 v10, v13, 4, v10
	v_lshl_add_u64 v[8:9], s[0:1], 0, v[8:9]
	v_lshl_add_u64 v[10:11], s[22:23], 0, v[10:11]
	s_mov_b32 s27, 64
	v_add_u32_e32 v13, v15, v14
	v_mov_b32_e32 v224, 0
	v_mov_b32_e32 v225, 0
	v_mov_b32_e32 v226, 0
	v_mov_b32_e32 v227, 0
	v_mov_b32_e32 v220, 0
	v_mov_b32_e32 v221, 0
	v_mov_b32_e32 v222, 0
	v_mov_b32_e32 v223, 0
	s_and_saveexec_b64 s[30:31], s[6:7]
	v_add_co_u32_e32 v224, vcc, 0xfffe0000, v8
	s_nop 1
	v_addc_co_u32_e32 v225, vcc, -1, v9, vcc
	global_load_dwordx4 v[224:227], v[224:225], off nt
	global_load_dwordx4 v[220:223], v[8:9], off nt
	s_or_b64 exec, exec, s[30:31]
	s_waitcnt vmcnt(2)
	s_branch .LBB0_66
.LBB0_66:
	v_cvt_f16_f32_e32 v4, v4
	v_cvt_f16_f32_e32 v0, v0
	v_cvt_f16_f32_e32 v5, v5
	v_cvt_f16_f32_e32 v1, v1
	s_waitcnt lgkmcnt(0)
	s_barrier
	v_cvt_f16_f32_e32 v6, v6
	v_cvt_f16_f32_e32 v2, v2
	v_cvt_f16_f32_e32 v7, v7
	v_cvt_f16_f32_e32 v3, v3
	ds_write_b16 v13, v4
	ds_write_b16 v13, v5 offset:144
	ds_write_b16 v13, v6 offset:288
	ds_write_b16 v13, v7 offset:432
	ds_write_b16 v13, v0 offset:64
	ds_write_b16 v13, v1 offset:208
	ds_write_b16 v13, v2 offset:352
	ds_write_b16 v13, v3 offset:496
	s_waitcnt lgkmcnt(0)
	s_barrier
	ds_read_b128 v[14:17], v12
	s_cmpk_gt_u32 s27, 0x3bf
	s_cselect_b64 s[0:1], -1, 0
	s_waitcnt lgkmcnt(0)
	global_store_dwordx4 v[10:11], v[14:17], off offset:-128
	s_and_b64 vcc, exec, s[0:1]
	s_cbranch_vccnz .Lc66_lastq
	v_mov_b32_e32 v4, 0
	v_mov_b32_e32 v5, 0
	v_mov_b32_e32 v6, 0
	v_mov_b32_e32 v7, 0
	v_mov_b32_e32 v0, 0
	v_mov_b32_e32 v1, 0
	v_mov_b32_e32 v2, 0
	v_mov_b32_e32 v3, 0
	s_and_saveexec_b64 s[30:31], s[6:7]
	s_mov_b64 s[98:99], 0x20000
	v_lshl_add_u64 v[4:5], v[8:9], 0, s[98:99]
	global_load_dwordx4 v[4:7], v[4:5], off nt
	s_mov_b64 s[100:101], 0x40000
	v_lshl_add_u64 v[0:1], v[8:9], 0, s[100:101]
	global_load_dwordx4 v[0:3], v[0:1], off nt
	s_or_b64 exec, exec, s[30:31]
	s_waitcnt vmcnt(3)
	s_branch .Lc66_q

; DI float h2f(bf16_t v) { return (float)__builtin_bit_cast(_Float16, v); }
; DI float bf2f(bf16_t v) { return __uint_as_float(((unsigned)v) << 16); }
; DI void lds_barrier() { asm volatile("s_waitcnt lgkmcnt(0)\n\ts_barrier" ::: "memory"); }
;     ...
;     lds_barrier();
; #pragma unroll
;     for (int rr = 0; rr < 2; ++rr) { const int k = k0 + kr + rr * 32; const float gk = g ? g[k] : 1.0f, bk = b ? b[k] : 0.0f;
; #pragma unroll
;       for (int j = 0; j < 4; ++j) { const bf16_t v = perm ? f2h(w[rr][j] * gk) : f2bf(w[rr][j] * gk); tile[(nc + j) * 72 + kr + rr * 32] = v; s1[j] += perm ? h2f(v) : bf2f(v); s2[j] += bk * w[rr][j]; } }
;     if (k0 + 64 < kend) {
; #pragma unroll
;       for (int rr = 0; rr < 2; ++rr) w[rr] = colok ? *(const f32x4*)(src + (size_t)(k0 + 64 + kr + rr * 32) * ldn + n0 + nc) : (f32x4){0.f, 0.f, 0.f, 0.f};
;     }
.Lc66_q:
	v_cvt_f16_f32_e32 v18, v224
	v_cvt_f16_f32_e32 v19, v225
	v_cvt_f16_f32_e32 v20, v226
	v_cvt_f16_f32_e32 v21, v227
	v_cvt_f16_f32_e32 v14, v220
	v_cvt_f16_f32_e32 v15, v221
	v_cvt_f16_f32_e32 v16, v222
	v_cvt_f16_f32_e32 v17, v223
	s_waitcnt lgkmcnt(0)
	s_barrier
	ds_write_b16 v13, v18
	ds_write_b16 v13, v19 offset:144
	ds_write_b16 v13, v20 offset:288
	ds_write_b16 v13, v21 offset:432
	ds_write_b16 v13, v14 offset:64
	ds_write_b16 v13, v15 offset:208
	ds_write_b16 v13, v16 offset:352
	ds_write_b16 v13, v17 offset:496
	s_and_b64 vcc, exec, s[0:1]
	s_cbranch_vccnz .Lc66_65
	s_cmpk_lt_u32 s27, 0x380
	s_cbranch_scc0 .Lc66_65
	v_mov_b32_e32 v224, 0
	v_mov_b32_e32 v225, 0
	v_mov_b32_e32 v226, 0
	v_mov_b32_e32 v227, 0
	v_mov_b32_e32 v220, 0
	v_mov_b32_e32 v221, 0
	v_mov_b32_e32 v222, 0
	v_mov_b32_e32 v223, 0
	s_and_saveexec_b64 s[30:31], s[6:7]
	s_mov_b64 s[98:99], 0x60000
	v_lshl_add_u64 v[224:225], v[8:9], 0, s[98:99]
	global_load_dwordx4 v[224:227], v[224:225], off nt
	s_mov_b64 s[100:101], 0x80000
	v_lshl_add_u64 v[220:221], v[8:9], 0, s[100:101]
	global_load_dwordx4 v[220:223], v[220:221], off nt
	s_or_b64 exec, exec, s[30:31]

; DI int lane_id_() { int l; asm volatile("v_mbcnt_lo_u32_b32 %0, -1, 0\n\tv_mbcnt_hi_u32_b32 %0, -1, %0" : "=v"(l)); return l; }
;     ...
;   int tid_ = wv * 64 + lane_id_(); asm volatile("" : "+v"(tid_)); const int tid = tid_, kr = tid >> 4, nc = (tid & 15) * 4;
;   const bool colok = (n0 + nc) < nvalid;
;   float s1[4] = {0.f, 0.f, 0.f, 0.f}, s2[4] = {0.f, 0.f, 0.f, 0.f};
;   f32x4 w[2];
; #pragma unroll
;   for (int rr = 0; rr < 2; ++rr) w[rr] = colok ? *(const f32x4*)(src + (size_t)(kbeg + kr + rr * 32) * ldn + n0 + nc) : (f32x4){0.f, 0.f, 0.f, 0.f};
; DI void convert_phase(int wv, const P& p_, int L, LAS unsigned char* lds) {
;     ...
;     } else if (j < 272 + nin) {
;       const int s = j - 272; const float* lg = p.ln_gain + (size_t)(L * 3) * DM; const float* lbias = p.ln_bias + (size_t)(L * 3) * DM;
;       const float* src = kind == 0 ? p.nsa_win + (size_t)slot * DM * 2608 : (kind == 1 ? p.hg_win + (size_t)slot * DM * 4096 : p.swa_win + (size_t)slot * DM * 1280);
;       const int ldn = kind == 0 ? 2608 : (kind == 1 ? 4096 : 1280);
;       float* cbase = (float*)(ws + C_IN);
;       conv_strip(wv, lds, src, ldn, DM, s * 64, ldn, (bf16_t*)(ws + W_IN), s * 64, lg, lbias, cbase, cbase + 4096);
.LBB0_77:
	s_andn2_b64 vcc, exec, s[0:1]
	s_cbranch_vccnz .LBB0_102
	s_lshl_b32 s0, s87, 6
	s_add_i32 s84, s0, 0xffffbc00
	s_waitcnt vmcnt(1)
	v_mbcnt_lo_u32_b32 v0, -1, 0
	v_mbcnt_hi_u32_b32 v0, -1, v0
	s_lshl_b64 s[0:1], s[84:85], 2
	v_add_u32_e32 v33, s69, v0
	s_add_u32 s0, s49, s0
	v_lshlrev_b32_e32 v0, 2, v33
	v_and_b32_e32 v10, 60, v0
	v_or_b32_e32 v0, s84, v10
	s_addc_u32 s1, s43, s1
	v_lshlrev_b32_e32 v26, 2, v10
	v_mov_b32_e32 v27, v32
	v_ashrrev_i32_e32 v24, 4, v33
	v_cmp_gt_i32_e64 s[6:7], s42, v0
	v_lshl_add_u64 v[8:9], s[0:1], 0, v[26:27]
	v_mov_b32_e32 v4, 0
	v_mov_b32_e32 v0, 0
	v_mov_b32_e32 v1, 0
	v_mov_b32_e32 v2, 0
	v_mov_b32_e32 v3, 0
	s_and_saveexec_b64 s[0:1], s[6:7]
	s_cbranch_execz .LBB0_80
	v_mad_i64_i32 v[0:1], s[30:31], v24, s42, 0
	v_lshl_add_u64 v[0:1], v[0:1], 2, v[8:9]
	global_load_dwordx4 v[0:3], v[0:1], off nt
.LBB0_80:
	s_or_b64 exec, exec, s[0:1]
	v_mov_b32_e32 v5, 0
	v_mov_b32_e32 v6, 0
	v_mov_b32_e32 v7, 0
	s_and_saveexec_b64 s[0:1], s[6:7]
	s_cbranch_execz .LBB0_82
	v_add_u32_e32 v4, 32, v24
	v_mad_i64_i32 v[4:5], s[30:31], v4, s42, 0
	v_lshl_add_u64 v[4:5], v[4:5], 2, v[8:9]
	global_load_dwordx4 v[4:7], v[4:5], off nt

;     ...
;     if (k0 + 64 < kend) {
; #pragma unroll
;       for (int rr = 0; rr < 2; ++rr) w[rr] = colok ? *(const f32x4*)(src + (size_t)(k0 + 64 + kr + rr * 32) * ldn + n0 + nc) : (f32x4){0.f, 0.f, 0.f, 0.f};
;     }
.Lconv83_nb0:
	s_waitcnt vmcnt(0)
	v_mov_b32_e32 v244, 0
	v_mov_b32_e32 v245, 0
	v_mov_b32_e32 v246, 0
	v_mov_b32_e32 v247, 0
	v_mov_b32_e32 v248, 0
	v_mov_b32_e32 v249, 0
	v_mov_b32_e32 v250, 0
	v_mov_b32_e32 v251, 0
	s_and_saveexec_b64 s[30:31], s[6:7]
	v_lshl_add_u64 v[244:245], v[34:35], 0, v[30:31]
	v_lshl_add_u64 v[248:249], v[34:35], 0, v[36:37]
	global_load_dwordx4 v[244:247], v[244:245], off nt
	s_nop 0
	global_load_dwordx4 v[248:251], v[248:249], off nt
	s_or_b64 exec, exec, s[30:31]

;     ...
;     if (k0 + 64 < kend) {
; #pragma unroll
;       for (int rr = 0; rr < 2; ++rr) w[rr] = colok ? *(const f32x4*)(src + (size_t)(k0 + 64 + kr + rr * 32) * ldn + n0 + nc) : (f32x4){0.f, 0.f, 0.f, 0.f};
;     }
.Lc83a_nb:
	s_cmpk_lt_u32 s27, 0x380
	s_cbranch_scc0 .Lc83a_97
	v_mov_b32_e32 v220, 0
	v_mov_b32_e32 v221, 0
	v_mov_b32_e32 v222, 0
	v_mov_b32_e32 v223, 0
	v_mov_b32_e32 v224, 0
	v_mov_b32_e32 v225, 0
	v_mov_b32_e32 v226, 0
	v_mov_b32_e32 v227, 0
	s_and_saveexec_b64 s[30:31], s[6:7]
	v_lshl_add_u64 v[220:221], v[34:35], 0, v[30:31]
	v_lshl_add_u64 v[224:225], v[34:35], 0, v[36:37]
	v_lshl_add_u64 v[220:221], v[220:221], 0, s[82:83]
	v_lshl_add_u64 v[224:225], v[224:225], 0, s[82:83]
	global_load_dwordx4 v[220:223], v[220:221], off nt
	s_nop 0
	global_load_dwordx4 v[224:227], v[224:225], off nt
	s_or_b64 exec, exec, s[30:31]

;     ...
;     if (k0 + 64 < kend) {
; #pragma unroll
;       for (int rr = 0; rr < 2; ++rr) w[rr] = colok ? *(const f32x4*)(src + (size_t)(k0 + 64 + kr + rr * 32) * ldn + n0 + nc) : (f32x4){0.f, 0.f, 0.f, 0.f};
;     }
.Lc83b_nb:
	s_cmpk_lt_u32 s27, 0x380
	s_cbranch_scc0 .Lc83b_97
	v_mov_b32_e32 v244, 0
	v_mov_b32_e32 v245, 0
	v_mov_b32_e32 v246, 0
	v_mov_b32_e32 v247, 0
	v_mov_b32_e32 v248, 0
	v_mov_b32_e32 v249, 0
	v_mov_b32_e32 v250, 0
	v_mov_b32_e32 v251, 0
	s_and_saveexec_b64 s[30:31], s[6:7]
	v_lshl_add_u64 v[244:245], v[34:35], 0, v[30:31]
	v_lshl_add_u64 v[248:249], v[34:35], 0, v[36:37]
	v_lshl_add_u64 v[244:245], v[244:245], 0, s[82:83]
	v_lshl_add_u64 v[248:249], v[248:249], 0, s[82:83]
	global_load_dwordx4 v[244:247], v[244:245], off nt
	s_nop 0
	global_load_dwordx4 v[248:251], v[248:249], off nt
	s_or_b64 exec, exec, s[30:31]

; #define LAS __attribute__((address_space(3)))
; DI float h2f(bf16_t v) { return (float)__builtin_bit_cast(_Float16, v); }
; DI float bf2f(bf16_t v) { return __uint_as_float(((unsigned)v) << 16); }
; DI int lane_id_() { int l; asm volatile("v_mbcnt_lo_u32_b32 %0, -1, 0\n\tv_mbcnt_hi_u32_b32 %0, -1, %0" : "=v"(l)); return l; }
; DI void lds_barrier() { asm volatile("s_waitcnt lgkmcnt(0)\n\ts_barrier" ::: "memory"); }
;     ...
;   int tid_ = wv * 64 + lane_id_(); asm volatile("" : "+v"(tid_)); const int tid = tid_, kr = tid >> 4, nc = (tid & 15) * 4;
;   const bool colok = (n0 + nc) < nvalid;
;   float s1[4] = {0.f, 0.f, 0.f, 0.f}, s2[4] = {0.f, 0.f, 0.f, 0.f};
;   f32x4 w[2];
; #pragma unroll
;   for (int rr = 0; rr < 2; ++rr) w[rr] = colok ? *(const f32x4*)(src + (size_t)(kbeg + kr + rr * 32) * ldn + n0 + nc) : (f32x4){0.f, 0.f, 0.f, 0.f};
;   for (int k0 = kbeg; k0 < kend; k0 += 64) {
;     lds_barrier();
; #pragma unroll
;     for (int rr = 0; rr < 2; ++rr) { const int k = k0 + kr + rr * 32; const float gk = g ? g[k] : 1.0f, bk = b ? b[k] : 0.0f;
; #pragma unroll
;       for (int j = 0; j < 4; ++j) { const bf16_t v = perm ? f2h(w[rr][j] * gk) : f2bf(w[rr][j] * gk); tile[(nc + j) * 72 + kr + rr * 32] = v; s1[j] += perm ? h2f(v) : bf2f(v); s2[j] += bk * w[rr][j]; } }
;     if (k0 + 64 < kend) {
; #pragma unroll
;       for (int rr = 0; rr < 2; ++rr) w[rr] = colok ? *(const f32x4*)(src + (size_t)(k0 + 64 + kr + rr * 32) * ldn + n0 + nc) : (f32x4){0.f, 0.f, 0.f, 0.f};
;     }
;     lds_barrier();
;     { const int n = tid >> 3, kc = (tid & 7) * 8; const int cc = n & 31, slot = (n & 32) + (perm ? 16 * ((cc >> 2) & 1) + 4 * (cc >> 3) + (cc & 3) : cc);
;       *(u32x4*)(dst + (size_t)(dstrow0 + slot) * K + k0 + kc) = *(const LAS u32x4*)(tile + n * 72 + kc); }
; DI void convert_phase(int wv, const P& p_, int L, LAS unsigned char* lds) {
;     ...
;       } else {
;         const int s = (jj - 88) / 3, kc = (jj - 88) % 3;
;         const float* src = (f == 0 ? p.f1d : p.f2d) + (size_t)L * DFF * DM;
;         conv_strip(wv, lds, src, DM, DFF, s * 64, DM, (bf16_t*)(ws + (f == 0 ? W_D1 : W_D2)), s * 64, nullptr, nullptr, nullptr, nullptr, true, kc * 960, kc == 2 ? DFF : kc * 960 + 960);
.LBB0_103:
	s_andn2_b64 vcc, exec, s[0:1]
	s_cbranch_vccnz .LBB0_38
	s_mul_hi_i32 s0, s87, 0x78787879
	s_lshr_b32 s1, s0, 31
	s_ashr_i32 s0, s0, 6
	s_add_i32 s0, s0, s1
	s_mulk_i32 s0, 0x88
	s_sub_i32 s27, s87, s0
	s_add_i32 s0, s87, 0x87
	s_cmpk_lt_u32 s0, 0x10f
	s_cselect_b64 s[78:79], -1, 0
	s_cmpk_gt_i32 s27, 0x57
	s_mov_b64 s[0:1], -1
	s_cbranch_scc0 .LBB0_111
	s_add_i32 s29, s27, 0xffa8
	s_and_b32 s0, s29, 0xff
	s_mul_i32 s1, s0, 0xab
	s_bfe_u32 s1, s1, 0x70009
	s_mul_i32 s30, s1, 3
	s_sub_i32 s29, s29, s30
	s_and_b32 s30, s29, 0xff
	s_mul_i32 s29, s30, 0x3c0
	s_add_i32 s31, s29, 0x3c0
	s_cmp_lg_u32 s30, 2
	s_cselect_b32 s30, s31, 0xb00
	s_waitcnt vmcnt(1)
	v_mbcnt_lo_u32_b32 v0, -1, 0
	v_mbcnt_hi_u32_b32 v0, -1, v0
	s_cmp_ge_u32 s29, s30
	v_add_u32_e32 v8, s69, v0
	s_cbranch_scc1 .LBB0_110
	v_readlane_b32 s60, v252, 16
	v_readlane_b32 s61, v252, 17
	v_readlane_b32 s62, v252, 18
	v_readlane_b32 s63, v252, 19
	v_readlane_b32 s64, v252, 20
	v_readlane_b32 s65, v252, 21
	v_readlane_b32 s66, v252, 22
	v_readlane_b32 s67, v252, 23
	v_readlane_b32 s68, v252, 24
	v_readlane_b32 s69, v252, 25
	v_readlane_b32 s70, v252, 26
	v_readlane_b32 s71, v252, 27
	s_and_b32 s1, 0xffff, s1
	v_readlane_b32 s72, v252, 28
	v_readlane_b32 s73, v252, 29
	v_readlane_b32 s74, v252, 30
	v_readlane_b32 s75, v252, 31
	s_mov_b64 s[60:61], s[64:65]
	v_readlane_b32 s4, v252, 32
	s_and_b64 s[34:35], s[78:79], exec
	s_mov_b64 s[62:63], s[66:67]
	s_mov_b64 s[64:65], s[68:69]
	s_mov_b64 s[66:67], s[70:71]
	s_mov_b64 s[68:69], s[72:73]
	v_readlane_b32 s6, v252, 34
	v_readlane_b32 s7, v252, 35
	s_cselect_b32 s36, s68, s6
	s_cselect_b32 s31, s69, s7
	s_add_u32 s34, s36, s93
	s_addc_u32 s35, s31, 0
	s_lshl_b32 s37, s1, 6
	v_ashrrev_i32_e32 v12, 4, v8
	v_lshlrev_b32_e32 v0, 2, v8
	s_lshl_b32 s38, s1, 8
	v_and_b32_e32 v9, 60, v0
	s_add_u32 s34, s34, s38
	v_add_u32_e32 v2, s29, v12
	s_addc_u32 s35, s35, 0
	v_lshlrev_b32_e32 v0, 2, v9
	v_mov_b32_e32 v1, v32
	v_ashrrev_i32_e32 v3, 31, v2
	v_lshl_add_u64 v[0:1], s[34:35], 0, v[0:1]
	v_lshlrev_b64 v[2:3], 12, v[2:3]
	v_lshl_add_u64 v[0:1], v[0:1], 0, v[2:3]
	s_mov_b32 s34, 0x20000
	v_add_co_u32_e32 v2, vcc, s34, v0
	v_ashrrev_i32_e32 v10, 3, v8
	s_nop 0
	v_addc_co_u32_e32 v3, vcc, 0, v1, vcc
	global_load_dwordx4 v[4:7], v[2:3], off nt
	s_nop 0
	global_load_dwordx4 v[0:3], v[0:1], off nt
	v_lshrrev_b32_e32 v13, 1, v10
	v_lshlrev_b32_e32 v16, 4, v8
	v_lshlrev_b32_e32 v11, 2, v10
	v_and_b32_e32 v13, 12, v13
	v_mul_lo_u32 v14, v10, s90
	v_and_b32_e32 v17, 0x70, v16
	v_and_b32_e32 v11, 16, v11
	v_add3_u32 v14, 0, v14, v17
	v_mul_u32_u24_e32 v17, 0x90, v9
	v_and_or_b32 v9, v10, 35, v13
	s_and_b64 s[34:35], s[78:79], exec
	s_mov_b32 s6, 0x1b80000
	v_or3_b32 v9, v9, v11, s37
	s_cselect_b32 s34, 0xb00000, s6
	v_mul_u32_u24_e32 v10, 0xb00, v9
	v_and_b32_e32 v8, 7, v8
	v_lshl_or_b32 v8, v8, 4, s34
	v_mov_b32_e32 v9, v32
	v_lshlrev_b32_e32 v10, 1, v10
	v_mov_b32_e32 v11, v32
	s_mul_i32 s37, s0, 0x3c0
	v_lshl_add_u64 v[8:9], v[8:9], 0, v[10:11]
	s_lshl_b32 s34, s29, 1
	s_mulk_i32 s1, 0xb40
	v_add_u32_e32 v10, s37, v12
	v_lshl_add_u32 v15, v12, 1, 0
	s_add_u32 s34, s94, s34
	v_subrev_u32_e32 v12, s1, v10
	s_addc_u32 s35, s95, 0
	v_readlane_b32 s6, v255, 6
	v_add_u32_e32 v10, 0x60, v12
	v_lshl_add_u64 v[8:9], s[34:35], 0, v[8:9]
	v_readlane_b32 s7, v255, 7
	s_add_u32 s34, s36, s6
	v_ashrrev_i32_e32 v11, 31, v10
	s_mul_hi_u32 s0, s0, 0x55555556
	v_ashrrev_i32_e32 v13, 31, v12
	s_addc_u32 s35, s31, s7
	v_lshlrev_b64 v[10:11], 12, v[10:11]
	s_lshl_b32 s84, s0, 8
	v_readlane_b32 s0, v255, 14
	v_lshlrev_b64 v[12:13], 12, v[12:13]
	v_readlane_b32 s5, v252, 33
	v_lshl_add_u64 v[10:11], v[10:11], 0, s[84:85]
	v_and_b32_e32 v16, 0xf0, v16
	v_readlane_b32 s1, v255, 15
	s_add_u32 s0, s36, s0
	v_lshl_add_u64 v[12:13], v[12:13], 0, s[84:85]
	s_mov_b64 s[70:71], s[74:75]
	v_readlane_b32 s72, v255, 24
	v_readlane_b32 s4, v252, 56
	v_or_b32_e32 v10, v10, v16
	s_addc_u32 s1, s31, s1
	v_or_b32_e32 v12, v12, v16
	s_mov_b32 s60, 0xf149f2ca
	s_movk_i32 s65, 0xa00
	v_readlane_b32 s64, v255, 30
	v_readlane_b32 s75, v255, 28
	v_readlane_b32 s74, v255, 27
	v_readlane_b32 s67, v255, 26
	v_readlane_b32 s73, v255, 25
	v_readlane_b32 s66, v255, 23
	v_readlane_b32 s5, v252, 57
	s_mov_b32 s69, s48
	s_mov_b32 s68, s44
	v_lshl_add_u64 v[10:11], s[34:35], 0, v[10:11]
	v_lshl_add_u64 v[12:13], s[0:1], 0, v[12:13]
	v_add_u32_e32 v15, v15, v17
	v_readlane_b32 s8, v252, 36
	v_readlane_b32 s9, v252, 37
	v_readlane_b32 s10, v252, 38
	v_readlane_b32 s11, v252, 39
	v_readlane_b32 s12, v252, 40
	v_readlane_b32 s13, v252, 41
	v_readlane_b32 s14, v252, 42
	v_readlane_b32 s15, v252, 43
	v_readlane_b32 s16, v252, 44
	v_readlane_b32 s17, v252, 45
	v_readlane_b32 s18, v252, 46
	v_readlane_b32 s19, v252, 47
	s_mov_b64 s[100:101], 0x40000
	global_load_dwordx4 v[244:247], v[12:13], off nt
	s_nop 0
	global_load_dwordx4 v[248:251], v[10:11], off nt
	s_waitcnt vmcnt(2)
	s_branch .LBB0_108
.LBB0_108:
	v_cvt_f16_f32_e32 v16, v0
	v_cvt_f16_f32_e32 v17, v1
	v_cvt_f16_f32_e32 v18, v2
	v_cvt_f16_f32_e32 v19, v3
	s_waitcnt lgkmcnt(0)
	s_barrier
	ds_write_b16 v15, v16
	ds_write_b16 v15, v17 offset:144
	ds_write_b16 v15, v18 offset:288
	ds_write_b16 v15, v19 offset:432
	v_cvt_f16_f32_e32 v16, v4
	s_add_i32 s29, s29, 64
	v_cvt_f16_f32_e32 v17, v5
	s_cmp_ge_u32 s29, s30
	v_cvt_f16_f32_e32 v18, v6
	s_cselect_b64 s[0:1], -1, 0
	v_cvt_f16_f32_e32 v19, v7
	s_and_b64 vcc, exec, s[0:1]
	ds_write_b16 v15, v16 offset:64
	ds_write_b16 v15, v17 offset:208
	ds_write_b16 v15, v18 offset:352
	ds_write_b16 v15, v19 offset:496
	s_cbranch_vccnz .Lc108a_107
	s_add_i32 s98, s29, 64
	s_cmp_lt_u32 s98, s30
	s_cbranch_scc0 .Lc108a_107
	v_lshl_add_u64 v[220:221], v[12:13], 0, s[100:101]
	v_lshl_add_u64 v[224:225], v[10:11], 0, s[100:101]
	global_load_dwordx4 v[220:223], v[220:221], off nt
	s_nop 0
	global_load_dwordx4 v[224:227], v[224:225], off nt

; DI float h2f(bf16_t v) { return (float)__builtin_bit_cast(_Float16, v); }
; DI float bf2f(bf16_t v) { return __uint_as_float(((unsigned)v) << 16); }
; DI void lds_barrier() { asm volatile("s_waitcnt lgkmcnt(0)\n\ts_barrier" ::: "memory"); }
;     ...
;     lds_barrier();
; #pragma unroll
;     for (int rr = 0; rr < 2; ++rr) { const int k = k0 + kr + rr * 32; const float gk = g ? g[k] : 1.0f, bk = b ? b[k] : 0.0f;
; #pragma unroll
;       for (int j = 0; j < 4; ++j) { const bf16_t v = perm ? f2h(w[rr][j] * gk) : f2bf(w[rr][j] * gk); tile[(nc + j) * 72 + kr + rr * 32] = v; s1[j] += perm ? h2f(v) : bf2f(v); s2[j] += bk * w[rr][j]; } }
;     if (k0 + 64 < kend) {
; #pragma unroll
;       for (int rr = 0; rr < 2; ++rr) w[rr] = colok ? *(const f32x4*)(src + (size_t)(k0 + 64 + kr + rr * 32) * ldn + n0 + nc) : (f32x4){0.f, 0.f, 0.f, 0.f};
;     }
.Lc108b_top:
	v_cvt_f16_f32_e32 v16, v0
	v_cvt_f16_f32_e32 v17, v1
	v_cvt_f16_f32_e32 v18, v2
	v_cvt_f16_f32_e32 v19, v3
	s_waitcnt lgkmcnt(0)
	s_barrier
	ds_write_b16 v15, v16
	ds_write_b16 v15, v17 offset:144
	ds_write_b16 v15, v18 offset:288
	ds_write_b16 v15, v19 offset:432
	v_cvt_f16_f32_e32 v16, v4
	s_add_i32 s29, s29, 64
	v_cvt_f16_f32_e32 v17, v5
	s_cmp_ge_u32 s29, s30
	v_cvt_f16_f32_e32 v18, v6
	s_cselect_b64 s[0:1], -1, 0
	v_cvt_f16_f32_e32 v19, v7
	s_and_b64 vcc, exec, s[0:1]
	ds_write_b16 v15, v16 offset:64
	ds_write_b16 v15, v17 offset:208
	ds_write_b16 v15, v18 offset:352
	ds_write_b16 v15, v19 offset:496
	s_cbranch_vccnz .Lc108b_107
	s_add_i32 s98, s29, 64
	s_cmp_lt_u32 s98, s30
	s_cbranch_scc0 .Lc108b_107
	v_lshl_add_u64 v[244:245], v[12:13], 0, s[100:101]
	v_lshl_add_u64 v[248:249], v[10:11], 0, s[100:101]
	global_load_dwordx4 v[244:247], v[244:245], off nt
	s_nop 0
	global_load_dwordx4 v[248:251], v[248:249], off nt

; DI int lane_id_() { int l; asm volatile("v_mbcnt_lo_u32_b32 %0, -1, 0\n\tv_mbcnt_hi_u32_b32 %0, -1, %0" : "=v"(l)); return l; }
;     ...
;   int tid_ = wv * 64 + lane_id_(); asm volatile("" : "+v"(tid_)); const int tid = tid_, kr = tid >> 4, nc = (tid & 15) * 4;
;   const bool colok = (n0 + nc) < nvalid;
;   float s1[4] = {0.f, 0.f, 0.f, 0.f}, s2[4] = {0.f, 0.f, 0.f, 0.f};
;   f32x4 w[2];
; #pragma unroll
;   for (int rr = 0; rr < 2; ++rr) w[rr] = colok ? *(const f32x4*)(src + (size_t)(kbeg + kr + rr * 32) * ldn + n0 + nc) : (f32x4){0.f, 0.f, 0.f, 0.f};
; DI void convert_phase(int wv, const P& p_, int L, LAS unsigned char* lds) {
;     ...
;       const int f = j / 136, jj = j % 136;
;       const float* lg = p.ln_gain + (size_t)(L * 3 + (f == 0 ? -1 : 1)) * DM; const float* lbias = p.ln_bias + (size_t)(L * 3 + (f == 0 ? -1 : 1)) * DM;
;       const bool fold = !(L == 0 && f == 0);
;       float* cbase = (float*)(ws + (f == 0 ? C_GU1 : C_GU2));
;       if (jj < 88) {
;         const int up = jj / 44, s = jj % 44, n0 = s * 64;
;         const float* src = (f == 0 ? (up ? p.f1u : p.f1g) : (up ? p.f2u : p.f2g)) + (size_t)L * DM * DFF;
;         conv_strip(wv, lds, src, DFF, DM, n0, DFF, (bf16_t*)(ws + (f == 0 ? W_GU1 : W_GU2)), (n0 >> 7) * 256 + (n0 & 127) + up * 128, fold ? lg : nullptr, fold ? lbias : nullptr, cbase, cbase + 5632);
.LBB0_111:
	s_and_b64 vcc, exec, s[0:1]
	s_cbranch_vccz .LBB0_38
	s_sext_i32_i16 s29, s27
	s_and_b64 s[0:1], s[78:79], exec
	s_mulk_i32 s29, 0xba3
	s_cselect_b32 s90, -1, 1
	s_lshr_b32 s30, s29, 31
	s_ashr_i32 s29, s29, 17
	s_add_i32 s29, s29, s30
	s_sext_i32_i16 s35, s29
	s_mul_i32 s29, s29, 44
	s_sub_i32 s29, s27, s29
	s_sext_i32_i16 s29, s29
	s_and_b64 s[0:1], s[46:47], s[78:79]
	s_lshl_b32 s34, s29, 6
	s_add_i32 s27, s27, 43
	v_readlane_b32 s60, v252, 16
	v_readlane_b32 s4, v252, 32
	s_cmpk_lt_u32 s27, 0x57
	v_readlane_b32 s68, v252, 24
	v_readlane_b32 s69, v252, 25
	v_readlane_b32 s70, v252, 26
	v_readlane_b32 s71, v252, 27
	v_readlane_b32 s74, v252, 30
	v_readlane_b32 s75, v252, 31
	v_readlane_b32 s5, v252, 33
	s_cselect_b32 s27, s68, s70
	s_cselect_b32 s36, s69, s71
	s_cselect_b32 s37, s74, s4
	s_cselect_b32 s38, s75, s5
	s_and_b64 s[30:31], s[78:79], exec
	s_cselect_b32 s92, s27, s37
	s_mov_b32 s69, s48
	s_cselect_b32 s30, 0, 0x1080000
	s_cselect_b32 s91, s36, s38
	s_add_u32 s31, s92, s93
	s_addc_u32 s37, s91, 0
	s_lshl_b32 s27, s29, 7
	s_lshl_b32 s84, s35, 7
	s_waitcnt vmcnt(1)
	v_mbcnt_lo_u32_b32 v0, -1, 0
	v_mbcnt_hi_u32_b32 v0, -1, v0
	s_ashr_i32 s35, s34, 31
	v_add_u32_e32 v33, s69, v0
	s_and_b32 s27, s27, 0xffffff00
	s_and_b32 s29, s34, 64
	s_lshl_b64 s[34:35], s[34:35], 2
	v_lshlrev_b32_e32 v0, 2, v33
	v_and_b32_e32 v10, 60, v0
	s_add_u32 s36, s31, s34
	v_ashrrev_i32_e32 v24, 4, v33
	s_addc_u32 s37, s37, s35
	v_lshlrev_b32_e32 v26, 2, v10
	v_mov_b32_e32 v27, v32
	v_lshl_add_u64 v[0:1], s[36:37], 0, v[26:27]
	s_movk_i32 s4, 0x2c00
	v_add_u32_e32 v4, 32, v24
	v_mad_i64_i32 v[2:3], s[36:37], v24, s4, v[0:1]
	v_mad_i64_i32 v[4:5], s[36:37], v4, s4, v[0:1]
	global_load_dwordx4 v[0:3], v[2:3], off nt
	s_nop 0
	global_load_dwordx4 v[4:7], v[4:5], off nt
	v_readlane_b32 s6, v252, 34
	v_readlane_b32 s7, v252, 35
	v_mad_i64_i32 v[8:9], s[36:37], v24, s4, 0
	v_readlane_b32 s4, v252, 54
	v_readlane_b32 s6, v252, 58
	s_movk_i32 vcc_lo, 0x90
	v_readlane_b32 s5, v252, 55
	v_readlane_b32 s7, v252, 59
	v_ashrrev_i32_e32 v11, 3, v33
	v_lshlrev_b32_e32 v16, 4, v33
	s_nor_b64 s[36:37], s[0:1], s[4:5]
	s_nor_b64 s[38:39], s[0:1], s[6:7]
	v_mul_lo_u32 v15, v11, vcc_lo
	v_and_b32_e32 v16, 0x70, v16
	s_add_i32 s0, s84, s27
	v_lshlrev_b32_e32 v13, 2, v11
	v_lshrrev_b32_e32 v14, 1, v11
	v_add3_u32 v27, 0, v15, v16
	v_mul_u32_u24_e32 v15, 0x90, v10
	v_and_or_b32 v10, v11, 35, s0
	v_and_b32_e32 v13, 16, v13
	v_and_b32_e32 v14, 12, v14
	v_or_b32_e32 v10, s29, v10
	v_or3_b32 v10, v10, v13, v14
	v_ashrrev_i32_e32 v11, 31, v10
	s_mov_b32 s31, 0
	v_lshlrev_b64 v[10:11], 11, v[10:11]
	v_lshl_add_u64 v[10:11], s[30:31], 0, v[10:11]
	v_and_b32_e32 v13, 7, v33
	v_lshl_or_b32 v10, v13, 4, v10
	v_readlane_b32 s0, v255, 10
	v_lshl_add_u64 v[28:29], s[94:95], 0, v[10:11]
	v_readlane_b32 s1, v255, 11
	s_add_u32 s0, s92, s0
	v_and_b32_e32 v10, 15, v33
	s_addc_u32 s1, s91, s1
	v_lshl_or_b32 v8, v10, 4, v8
	v_lshl_add_u64 v[30:31], s[0:1], 0, v[8:9]
	v_readlane_b32 s0, v255, 12
	v_readlane_b32 s1, v255, 13
	s_add_u32 s0, s92, s0
	s_addc_u32 s1, s91, s1
	v_lshl_add_u64 v[34:35], s[0:1], 0, v[8:9]
	v_readlane_b32 s0, v255, 5
	s_add_i32 s0, s0, s90
	s_ashr_i32 s1, s0, 31
	v_ashrrev_i32_e32 v25, 31, v24
	s_lshl_b64 s[0:1], s[0:1], 12
	v_lshl_add_u64 v[8:9], v[24:25], 2, s[0:1]
	v_readlane_b32 s0, v254, 2
	v_readlane_b32 s1, v254, 3
	v_readlane_b32 s72, v252, 28
	v_readlane_b32 s73, v252, 29
	v_lshl_add_u64 v[36:37], s[0:1], 0, v[8:9]
	v_readlane_b32 s0, v254, 4
	v_readlane_b32 s1, v254, 5
	v_readlane_b32 s64, v252, 20
	v_readlane_b32 s65, v252, 21
	v_readlane_b32 s66, v252, 22
	v_readlane_b32 s67, v252, 23
	v_readlane_b32 s72, v255, 24
	v_readlane_b32 s4, v252, 56
	v_lshl_add_u32 v12, v24, 1, 0
	v_lshl_add_u64 v[38:39], s[0:1], 0, v[8:9]
	v_mov_b32_e32 v8, 0
	s_mov_b32 s60, 0xf149f2ca
	s_movk_i32 s65, 0xa00
	v_readlane_b32 s64, v255, 30
	v_readlane_b32 s67, v255, 26
	v_readlane_b32 s73, v255, 25
	v_readlane_b32 s66, v255, 23
	s_mov_b32 s68, s44
	v_readlane_b32 s74, v255, 27
	v_readlane_b32 s75, v255, 28
	v_readlane_b32 s5, v252, 57
	s_movk_i32 s91, 0x1600
	s_movk_i32 s90, 0x90
	v_add_u32_e32 v25, v12, v15
	v_mov_b32_e32 v9, v8
	v_mov_b32_e32 v10, v8
	v_mov_b32_e32 v11, v8
	v_mov_b32_e32 v12, v8
	v_mov_b32_e32 v13, v8
	v_mov_b32_e32 v14, v8
	v_mov_b32_e32 v15, v8
	s_mov_b64 s[6:7], 0xb0000
	v_readlane_b32 s61, v252, 17
	v_readlane_b32 s62, v252, 18
	v_readlane_b32 s63, v252, 19
	v_readlane_b32 s8, v252, 36
	v_readlane_b32 s9, v252, 37
	v_readlane_b32 s10, v252, 38
	v_readlane_b32 s11, v252, 39
	v_readlane_b32 s12, v252, 40
	v_readlane_b32 s13, v252, 41
	v_readlane_b32 s14, v252, 42
	v_readlane_b32 s15, v252, 43
	v_readlane_b32 s16, v252, 44
	v_readlane_b32 s17, v252, 45
	v_readlane_b32 s18, v252, 46
	v_readlane_b32 s19, v252, 47
	s_and_b64 vcc, exec, s[36:37]
	s_cbranch_vccz .Lconv113_ng0
	global_load_dword v216, v[38:39], off offset:-128
	global_load_dword v218, v[38:39], off

;     ...
;     if (k0 + 64 < kend) {
; #pragma unroll
;       for (int rr = 0; rr < 2; ++rr) w[rr] = colok ? *(const f32x4*)(src + (size_t)(k0 + 64 + kr + rr * 32) * ldn + n0 + nc) : (f32x4){0.f, 0.f, 0.f, 0.f};
;     }
.Lconv113_nb0:
	s_waitcnt vmcnt(0)
	s_add_u32 s98, s34, s6
	s_addc_u32 s99, s35, s7
	v_lshl_add_u64 v[244:245], v[34:35], 0, s[34:35]
	v_lshl_add_u64 v[248:249], v[30:31], 0, s[34:35]
	global_load_dwordx4 v[244:247], v[244:245], off nt
	s_nop 0
	global_load_dwordx4 v[248:251], v[248:249], off nt

;     ...
;     if (k0 + 64 < kend) {
; #pragma unroll
;       for (int rr = 0; rr < 2; ++rr) w[rr] = colok ? *(const f32x4*)(src + (size_t)(k0 + 64 + kr + rr * 32) * ldn + n0 + nc) : (f32x4){0.f, 0.f, 0.f, 0.f};
;     }
.Lc113a_nb:
	s_cmpk_lt_u32 s31, 0x380
	s_cbranch_scc0 .Lc113a_123
	v_lshl_add_u64 v[220:221], v[34:35], 0, s[98:99]
	v_lshl_add_u64 v[224:225], v[30:31], 0, s[98:99]
	global_load_dwordx4 v[220:223], v[220:221], off nt
	s_nop 0
	global_load_dwordx4 v[224:227], v[224:225], off nt

;     ...
;     if (k0 + 64 < kend) {
; #pragma unroll
;       for (int rr = 0; rr < 2; ++rr) w[rr] = colok ? *(const f32x4*)(src + (size_t)(k0 + 64 + kr + rr * 32) * ldn + n0 + nc) : (f32x4){0.f, 0.f, 0.f, 0.f};
;     }
.Lc113b_nb:
	s_cmpk_lt_u32 s31, 0x380
	s_cbranch_scc0 .Lc113b_123
	v_lshl_add_u64 v[244:245], v[34:35], 0, s[98:99]
	v_lshl_add_u64 v[248:249], v[30:31], 0, s[98:99]
	global_load_dwordx4 v[244:247], v[244:245], off nt
	s_nop 0
	global_load_dwordx4 v[248:251], v[248:249], off nt
